# c12 plus redundant compare-AND chains removed from the causal mask blocks of the forgetting-attention phase
# speedup vs baseline: 1.0142x; 1.0142x over previous
.LBB0_1312:
	v_bfe_u32 v176, v32, 5, 1
	v_lshlrev_b32_e32 v172, 2, v176
	v_sub_u32_e32 v178, v0, v172
	s_add_i32 s0, 0, 0x10800
	v_bitop3_b32 v0, v176, v32, 15 bitop3:0x78
	v_writelane_b32 v254, s8, 44
	s_add_i32 s78, s75, 31
	v_lshl_add_u32 v190, v176, 4, s0
	v_lshlrev_b32_e32 v33, 8, v171
	v_lshlrev_b32_e32 v66, 4, v0
	v_or_b32_e32 v50, v66, v33
	s_setprio 1
	s_add_i32 s63, s80, 3
	v_lshl_add_u32 v16, s63, 8, v190
	ds_read_b128 v[0:3], v16
	ds_read_b128 v[4:7], v16 offset:32
	ds_read_b128 v[8:11], v16 offset:64
	ds_read_b128 v[12:15], v16 offset:96
	ds_read_b128 v[34:37], v16 offset:128
	ds_read_b128 v[38:41], v16 offset:160
	ds_read_b128 v[42:45], v16 offset:192
	ds_read_b128 v[46:49], v16 offset:224
	s_lshl_b32 s2, s63, 6
	s_waitcnt lgkmcnt(4)
	v_pk_add_f32 v[30:31], v[14:15], v[180:181] op_sel:[0,1] op_sel_hi:[1,1] neg_lo:[0,1] neg_hi:[0,1]
	v_pk_add_f32 v[28:29], v[12:13], v[180:181] op_sel:[0,1] op_sel_hi:[1,1] neg_lo:[0,1] neg_hi:[0,1]
	v_pk_add_f32 v[26:27], v[10:11], v[180:181] op_sel:[0,1] op_sel_hi:[1,1] neg_lo:[0,1] neg_hi:[0,1]
	v_pk_add_f32 v[24:25], v[8:9], v[180:181] op_sel:[0,1] op_sel_hi:[1,1] neg_lo:[0,1] neg_hi:[0,1]
	v_pk_add_f32 v[22:23], v[6:7], v[180:181] op_sel:[0,1] op_sel_hi:[1,1] neg_lo:[0,1] neg_hi:[0,1]
	v_pk_add_f32 v[20:21], v[4:5], v[180:181] op_sel:[0,1] op_sel_hi:[1,1] neg_lo:[0,1] neg_hi:[0,1]
	v_pk_add_f32 v[18:19], v[2:3], v[180:181] op_sel:[0,1] op_sel_hi:[1,1] neg_lo:[0,1] neg_hi:[0,1]
	v_pk_add_f32 v[16:17], v[0:1], v[180:181] op_sel:[0,1] op_sel_hi:[1,1] neg_lo:[0,1] neg_hi:[0,1]
	s_waitcnt lgkmcnt(0)
	v_pk_add_f32 v[14:15], v[48:49], v[180:181] op_sel:[0,1] op_sel_hi:[1,1] neg_lo:[0,1] neg_hi:[0,1]
	v_pk_add_f32 v[12:13], v[46:47], v[180:181] op_sel:[0,1] op_sel_hi:[1,1] neg_lo:[0,1] neg_hi:[0,1]
	v_pk_add_f32 v[10:11], v[44:45], v[180:181] op_sel:[0,1] op_sel_hi:[1,1] neg_lo:[0,1] neg_hi:[0,1]
	v_pk_add_f32 v[8:9], v[42:43], v[180:181] op_sel:[0,1] op_sel_hi:[1,1] neg_lo:[0,1] neg_hi:[0,1]
	v_pk_add_f32 v[6:7], v[40:41], v[180:181] op_sel:[0,1] op_sel_hi:[1,1] neg_lo:[0,1] neg_hi:[0,1]
	v_pk_add_f32 v[4:5], v[38:39], v[180:181] op_sel:[0,1] op_sel_hi:[1,1] neg_lo:[0,1] neg_hi:[0,1]
	v_pk_add_f32 v[2:3], v[36:37], v[180:181] op_sel:[0,1] op_sel_hi:[1,1] neg_lo:[0,1] neg_hi:[0,1]
	v_pk_add_f32 v[0:1], v[34:35], v[180:181] op_sel:[0,1] op_sel_hi:[1,1] neg_lo:[0,1] neg_hi:[0,1]
	s_cmp_lg_u32 0, -1
	s_cselect_b32 s0, 0, 0
	v_add_u32_e32 v189, s0, v50
	ds_read_b128 v[34:37], v189 offset:0x8000
	ds_read_b128 v[38:41], v189 offset:0xa000
	v_xad_u32 v188, v50, 32, s0
	ds_read_b128 v[42:45], v188 offset:0x8000
	ds_read_b128 v[46:49], v188 offset:0xa000
	v_xad_u32 v187, v50, 64, s0
	ds_read_b128 v[50:53], v187 offset:0x8000
	s_movk_i32 s1, 0x60
	ds_read_b128 v[54:57], v187 offset:0xa000
	v_bitop3_b32 v58, v66, s1, v33 bitop3:0x36
	v_add_u32_e32 v184, s0, v58
	ds_read_b128 v[58:61], v184 offset:0x8000
	ds_read_b128 v[62:65], v184 offset:0xa000
	s_waitcnt lgkmcnt(7)
	v_mfma_f32_32x32x16_bf16 v[16:31], v[34:37], v[144:147], v[16:31]
	s_movk_i32 s1, 0x80
	v_bitop3_b32 v34, v66, s1, v33 bitop3:0x36
	v_add_u32_e32 v182, s0, v34
	ds_read_b128 v[34:37], v182 offset:0x8000
	s_waitcnt lgkmcnt(7)
	v_mfma_f32_32x32x16_bf16 v[0:15], v[38:41], v[144:147], v[0:15]
	ds_read_b128 v[38:41], v182 offset:0xa000
	s_waitcnt lgkmcnt(7)
	v_mfma_f32_32x32x16_bf16 v[16:31], v[42:45], v[136:139], v[16:31]
	s_movk_i32 s1, 0xa0
	v_bitop3_b32 v42, v66, s1, v33 bitop3:0x36
	v_add_u32_e32 v183, s0, v42
	ds_read_b128 v[42:45], v183 offset:0x8000
	s_waitcnt lgkmcnt(7)
	v_mfma_f32_32x32x16_bf16 v[0:15], v[46:49], v[136:139], v[0:15]
	ds_read_b128 v[46:49], v183 offset:0xa000
	s_waitcnt lgkmcnt(7)
	v_mfma_f32_32x32x16_bf16 v[16:31], v[50:53], v[128:131], v[16:31]
	s_movk_i32 s1, 0xc0
	v_bitop3_b32 v50, v66, s1, v33 bitop3:0x36
	v_add_u32_e32 v185, s0, v50
	ds_read_b128 v[50:53], v185 offset:0x8000
	s_waitcnt lgkmcnt(7)
	v_mfma_f32_32x32x16_bf16 v[0:15], v[54:57], v[128:131], v[0:15]
	ds_read_b128 v[54:57], v185 offset:0xa000
	s_waitcnt lgkmcnt(7)
	v_mfma_f32_32x32x16_bf16 v[16:31], v[58:61], v[124:127], v[16:31]
	s_movk_i32 s1, 0xe0
	v_bitop3_b32 v33, v66, s1, v33 bitop3:0x36
	v_add_u32_e32 v186, s0, v33
	ds_read_b128 v[58:61], v186 offset:0x8000
	s_waitcnt lgkmcnt(7)
	v_mfma_f32_32x32x16_bf16 v[0:15], v[62:65], v[124:127], v[0:15]
	ds_read_b128 v[62:65], v186 offset:0xa000
	s_waitcnt lgkmcnt(7)
	v_mfma_f32_32x32x16_bf16 v[16:31], v[34:37], v[120:123], v[16:31]
	s_waitcnt lgkmcnt(6)
	v_mfma_f32_32x32x16_bf16 v[0:15], v[38:41], v[120:123], v[0:15]
	s_waitcnt lgkmcnt(5)
	v_mfma_f32_32x32x16_bf16 v[16:31], v[42:45], v[116:119], v[16:31]
	s_waitcnt lgkmcnt(4)
	v_mfma_f32_32x32x16_bf16 v[0:15], v[46:49], v[116:119], v[0:15]
	s_waitcnt lgkmcnt(3)
	s_waitcnt vmcnt(1)
	v_mfma_f32_32x32x16_bf16 v[16:31], v[50:53], v[140:143], v[16:31]
	s_waitcnt lgkmcnt(2)
	v_mfma_f32_32x32x16_bf16 v[0:15], v[54:57], v[140:143], v[0:15]
	s_waitcnt lgkmcnt(1)
	s_waitcnt vmcnt(0)
	v_mfma_f32_32x32x16_bf16 v[16:31], v[58:61], v[132:135], v[16:31]
	s_waitcnt lgkmcnt(0)
	v_mfma_f32_32x32x16_bf16 v[0:15], v[62:65], v[132:135], v[0:15]
	s_setprio 0
	s_waitcnt lgkmcnt(0)
	s_barrier
	s_cmp_le_i32 s2, s78
	s_mov_b64 s[0:1], -1
	s_cbranch_scc0 .LBB0_1316
	s_or_b32 s0, s2, 63
	s_cmp_le_u32 s0, s75
	s_cbranch_scc1 .LBB0_1315
	v_subrev_u32_e32 v33, s2, v178
	v_cmp_gt_i32_e64 s[58:59], 26, v33
	v_cmp_gt_i32_e64 s[60:61], 27, v33
	v_cmp_gt_i32_e64 s[56:57], 25, v33
	v_cmp_gt_i32_e64 s[54:55], 24, v33
	v_cmp_gt_i32_e64 s[52:53], 19, v33
	v_cmp_gt_i32_e64 s[50:51], 18, v33
	v_cmp_gt_i32_e64 s[48:49], 17, v33
	v_cmp_gt_i32_e64 s[46:47], 16, v33
	v_cmp_gt_i32_e64 s[44:45], 11, v33
	v_cmp_gt_i32_e64 s[42:43], 10, v33
	v_cmp_gt_i32_e64 s[40:41], 9, v33
	v_cmp_gt_i32_e64 s[38:39], 8, v33
	v_cmp_gt_i32_e64 s[36:37], 3, v33
	v_cmp_gt_i32_e64 s[34:35], 2, v33
	v_cmp_gt_i32_e64 s[30:31], 1, v33
	v_cmp_gt_i32_e64 s[28:29], 0, v33
	v_cmp_gt_i32_e64 s[26:27], 58, v33
	v_cndmask_b32_e64 v16, v16, v169, s[28:29]
	v_cmp_gt_i32_e64 s[28:29], 59, v33
	v_cmp_gt_i32_e64 s[24:25], 57, v33
	v_cmp_gt_i32_e64 s[22:23], 56, v33
	v_cmp_gt_i32_e64 s[20:21], 51, v33
	v_cmp_gt_i32_e64 s[18:19], 50, v33
	v_cmp_gt_i32_e64 s[16:17], 49, v33
	v_cmp_gt_i32_e64 s[14:15], 48, v33
	v_cmp_gt_i32_e64 s[12:13], 43, v33
	v_cmp_gt_i32_e64 s[10:11], 42, v33
	v_cmp_gt_i32_e64 s[8:9], 41, v33
	v_cmp_gt_i32_e64 s[6:7], 40, v33
	v_cmp_gt_i32_e64 s[4:5], 35, v33
	v_cmp_gt_i32_e64 s[2:3], 34, v33
	v_cmp_gt_i32_e64 s[0:1], 33, v33
	v_cmp_gt_i32_e32 vcc, 32, v33
	v_cndmask_b32_e64 v31, v31, v169, s[60:61]
	v_cndmask_b32_e64 v30, v30, v169, s[58:59]
	v_cndmask_b32_e64 v29, v29, v169, s[56:57]
	v_cndmask_b32_e64 v28, v28, v169, s[54:55]
	v_cndmask_b32_e64 v27, v27, v169, s[52:53]
	v_cndmask_b32_e64 v26, v26, v169, s[50:51]
	v_cndmask_b32_e64 v25, v25, v169, s[48:49]
	v_cndmask_b32_e64 v24, v24, v169, s[46:47]
	v_cndmask_b32_e64 v23, v23, v169, s[44:45]
	v_cndmask_b32_e64 v22, v22, v169, s[42:43]
	v_cndmask_b32_e64 v21, v21, v169, s[40:41]
	v_cndmask_b32_e64 v20, v20, v169, s[38:39]
	v_cndmask_b32_e64 v19, v19, v169, s[36:37]
	v_cndmask_b32_e64 v18, v18, v169, s[34:35]
	v_cndmask_b32_e64 v17, v17, v169, s[30:31]
	v_cndmask_b32_e64 v15, v15, v169, s[28:29]
	v_cndmask_b32_e64 v14, v14, v169, s[26:27]
	v_cndmask_b32_e64 v13, v13, v169, s[24:25]
	v_cndmask_b32_e64 v12, v12, v169, s[22:23]
	v_cndmask_b32_e64 v11, v11, v169, s[20:21]
	v_cndmask_b32_e64 v10, v10, v169, s[18:19]
	v_cndmask_b32_e64 v9, v9, v169, s[16:17]
	v_cndmask_b32_e64 v8, v8, v169, s[14:15]
	v_cndmask_b32_e64 v7, v7, v169, s[12:13]
	v_cndmask_b32_e64 v6, v6, v169, s[10:11]
	v_cndmask_b32_e64 v5, v5, v169, s[8:9]
	v_cndmask_b32_e64 v4, v4, v169, s[6:7]
	v_cndmask_b32_e64 v3, v3, v169, s[4:5]
	v_cndmask_b32_e64 v2, v2, v169, s[2:3]
	v_cndmask_b32_e64 v1, v1, v169, s[0:1]
	v_cndmask_b32_e32 v0, v0, v169, vcc

.LBB0_1328:
	s_setprio 1
	ds_read_b128 v[64:67], v194 offset:256
	ds_read_b128 v[68:71], v194 offset:288
	ds_read_b128 v[72:75], v194 offset:320
	ds_read_b128 v[76:79], v194 offset:352
	ds_read_b128 v[196:199], v194 offset:384
	ds_read_b128 v[200:203], v194 offset:416
	ds_read_b128 v[204:207], v194 offset:448
	ds_read_b128 v[208:211], v194 offset:480
	s_add_i32 s0, s84, 64
	s_waitcnt lgkmcnt(4)
	v_pk_add_f32 v[94:95], v[78:79], v[180:181] op_sel:[0,1] op_sel_hi:[1,1] neg_lo:[0,1] neg_hi:[0,1]
	v_pk_add_f32 v[92:93], v[76:77], v[180:181] op_sel:[0,1] op_sel_hi:[1,1] neg_lo:[0,1] neg_hi:[0,1]
	v_pk_add_f32 v[90:91], v[74:75], v[180:181] op_sel:[0,1] op_sel_hi:[1,1] neg_lo:[0,1] neg_hi:[0,1]
	v_pk_add_f32 v[88:89], v[72:73], v[180:181] op_sel:[0,1] op_sel_hi:[1,1] neg_lo:[0,1] neg_hi:[0,1]
	v_pk_add_f32 v[86:87], v[70:71], v[180:181] op_sel:[0,1] op_sel_hi:[1,1] neg_lo:[0,1] neg_hi:[0,1]
	v_pk_add_f32 v[84:85], v[68:69], v[180:181] op_sel:[0,1] op_sel_hi:[1,1] neg_lo:[0,1] neg_hi:[0,1]
	v_pk_add_f32 v[82:83], v[66:67], v[180:181] op_sel:[0,1] op_sel_hi:[1,1] neg_lo:[0,1] neg_hi:[0,1]
	v_pk_add_f32 v[80:81], v[64:65], v[180:181] op_sel:[0,1] op_sel_hi:[1,1] neg_lo:[0,1] neg_hi:[0,1]
	s_waitcnt lgkmcnt(0)
	v_pk_add_f32 v[78:79], v[210:211], v[180:181] op_sel:[0,1] op_sel_hi:[1,1] neg_lo:[0,1] neg_hi:[0,1]
	v_pk_add_f32 v[76:77], v[208:209], v[180:181] op_sel:[0,1] op_sel_hi:[1,1] neg_lo:[0,1] neg_hi:[0,1]
	v_pk_add_f32 v[74:75], v[206:207], v[180:181] op_sel:[0,1] op_sel_hi:[1,1] neg_lo:[0,1] neg_hi:[0,1]
	v_pk_add_f32 v[72:73], v[204:205], v[180:181] op_sel:[0,1] op_sel_hi:[1,1] neg_lo:[0,1] neg_hi:[0,1]
	v_pk_add_f32 v[70:71], v[202:203], v[180:181] op_sel:[0,1] op_sel_hi:[1,1] neg_lo:[0,1] neg_hi:[0,1]
	v_pk_add_f32 v[68:69], v[200:201], v[180:181] op_sel:[0,1] op_sel_hi:[1,1] neg_lo:[0,1] neg_hi:[0,1]
	v_pk_add_f32 v[66:67], v[198:199], v[180:181] op_sel:[0,1] op_sel_hi:[1,1] neg_lo:[0,1] neg_hi:[0,1]
	v_pk_add_f32 v[64:65], v[196:197], v[180:181] op_sel:[0,1] op_sel_hi:[1,1] neg_lo:[0,1] neg_hi:[0,1]
	ds_read_b64_tr_b16 v[196:197], v179 offset:0
	ds_read_b64_tr_b16 v[198:199], v179 offset:0x800
	ds_read_b64_tr_b16 v[200:201], v179 offset:0x1000
	ds_read_b64_tr_b16 v[202:203], v179 offset:0x1800
	ds_read_b64_tr_b16 v[204:205], v179 offset:0x2000
	ds_read_b64_tr_b16 v[206:207], v179 offset:0x2800
	ds_read_b64_tr_b16 v[208:209], v179 offset:0x3000
	ds_read_b64_tr_b16 v[210:211], v179 offset:0x3800
	ds_read_b64_tr_b16 v[212:213], v179 offset:0x200
	ds_read_b64_tr_b16 v[214:215], v179 offset:0xa00
	ds_read_b64_tr_b16 v[216:217], v179 offset:0x1200
	ds_read_b64_tr_b16 v[218:219], v179 offset:0x1a00
	ds_read_b64_tr_b16 v[220:221], v179 offset:0x2200
	ds_read_b64_tr_b16 v[222:223], v179 offset:0x2a00
	ds_read_b64_tr_b16 v[224:225], v179 offset:0x3200
	ds_read_b64_tr_b16 v[226:227], v179 offset:0x3a00
	s_waitcnt lgkmcnt(14)
	s_nop 0
	v_mfma_f32_32x32x16_bf16 v[0:15], v[160:163], v[196:199], v[0:15]
	ds_read_b64_tr_b16 v[196:197], v179 offset:0x400
	ds_read_b64_tr_b16 v[198:199], v179 offset:0xc00
	s_waitcnt lgkmcnt(14)
	v_mfma_f32_32x32x16_bf16 v[0:15], v[156:159], v[200:203], v[0:15]
	ds_read_b64_tr_b16 v[200:201], v179 offset:0x1400
	ds_read_b64_tr_b16 v[202:203], v179 offset:0x1c00
	s_waitcnt lgkmcnt(14)
	v_mfma_f32_32x32x16_bf16 v[0:15], v[152:155], v[204:207], v[0:15]
	ds_read_b64_tr_b16 v[204:205], v179 offset:0x2400
	ds_read_b64_tr_b16 v[206:207], v179 offset:0x2c00
	s_waitcnt lgkmcnt(14)
	v_mfma_f32_32x32x16_bf16 v[0:15], v[148:151], v[208:211], v[0:15]
	ds_read_b64_tr_b16 v[208:209], v179 offset:0x3400
	ds_read_b64_tr_b16 v[210:211], v179 offset:0x3c00
	s_waitcnt lgkmcnt(14)
	v_mfma_f32_32x32x16_bf16 v[48:63], v[160:163], v[212:215], v[48:63]
	ds_read_b64_tr_b16 v[212:213], v179 offset:0x600
	ds_read_b64_tr_b16 v[214:215], v179 offset:0xe00
	s_waitcnt lgkmcnt(14)
	v_mfma_f32_32x32x16_bf16 v[48:63], v[156:159], v[216:219], v[48:63]
	ds_read_b64_tr_b16 v[216:217], v179 offset:0x1600
	ds_read_b64_tr_b16 v[218:219], v179 offset:0x1e00
	s_waitcnt lgkmcnt(14)
	v_mfma_f32_32x32x16_bf16 v[48:63], v[152:155], v[220:223], v[48:63]
	ds_read_b64_tr_b16 v[220:221], v179 offset:0x2600
	ds_read_b64_tr_b16 v[222:223], v179 offset:0x2e00
	s_waitcnt lgkmcnt(14)
	v_mfma_f32_32x32x16_bf16 v[48:63], v[148:151], v[224:227], v[48:63]
	ds_read_b64_tr_b16 v[224:225], v179 offset:0x3600
	ds_read_b64_tr_b16 v[226:227], v179 offset:0x3e00
	s_waitcnt lgkmcnt(14)
	v_mfma_f32_32x32x16_bf16 v[32:47], v[160:163], v[196:199], v[32:47]
	ds_read_b128 v[196:199], v189 offset:0xc000
	s_waitcnt lgkmcnt(13)
	v_mfma_f32_32x32x16_bf16 v[32:47], v[156:159], v[200:203], v[32:47]
	ds_read_b128 v[200:203], v189 offset:0xe000
	s_waitcnt lgkmcnt(12)
	v_mfma_f32_32x32x16_bf16 v[32:47], v[152:155], v[204:207], v[32:47]
	ds_read_b128 v[204:207], v188 offset:0xc000
	s_waitcnt lgkmcnt(11)
	v_mfma_f32_32x32x16_bf16 v[32:47], v[148:151], v[208:211], v[32:47]
	ds_read_b128 v[208:211], v188 offset:0xe000
	s_waitcnt lgkmcnt(10)
	v_mfma_f32_32x32x16_bf16 v[16:31], v[160:163], v[212:215], v[16:31]
	ds_read_b128 v[160:163], v187 offset:0xc000
	s_waitcnt lgkmcnt(9)
	v_mfma_f32_32x32x16_bf16 v[16:31], v[156:159], v[216:219], v[16:31]
	ds_read_b128 v[156:159], v187 offset:0xe000
	s_waitcnt lgkmcnt(8)
	v_mfma_f32_32x32x16_bf16 v[16:31], v[152:155], v[220:223], v[16:31]
	ds_read_b128 v[152:155], v184 offset:0xc000
	s_waitcnt lgkmcnt(7)
	v_mfma_f32_32x32x16_bf16 v[16:31], v[148:151], v[224:227], v[16:31]
	ds_read_b128 v[148:151], v184 offset:0xe000
	s_waitcnt lgkmcnt(7)
	v_mfma_f32_32x32x16_bf16 v[80:95], v[196:199], v[144:147], v[80:95]
	ds_read_b128 v[196:199], v182 offset:0xc000
	s_waitcnt lgkmcnt(7)
	v_mfma_f32_32x32x16_bf16 v[64:79], v[200:203], v[144:147], v[64:79]
	ds_read_b128 v[200:203], v182 offset:0xe000
	s_waitcnt lgkmcnt(7)
	v_mfma_f32_32x32x16_bf16 v[80:95], v[204:207], v[136:139], v[80:95]
	ds_read_b128 v[204:207], v183 offset:0xc000
	s_waitcnt lgkmcnt(7)
	v_mfma_f32_32x32x16_bf16 v[64:79], v[208:211], v[136:139], v[64:79]
	ds_read_b128 v[208:211], v183 offset:0xe000
	s_waitcnt lgkmcnt(7)
	v_mfma_f32_32x32x16_bf16 v[80:95], v[160:163], v[128:131], v[80:95]
	ds_read_b128 v[160:163], v185 offset:0xc000
	s_waitcnt lgkmcnt(7)
	v_mfma_f32_32x32x16_bf16 v[64:79], v[156:159], v[128:131], v[64:79]
	ds_read_b128 v[156:159], v185 offset:0xe000
	s_waitcnt lgkmcnt(7)
	v_mfma_f32_32x32x16_bf16 v[80:95], v[152:155], v[124:127], v[80:95]
	ds_read_b128 v[152:155], v186 offset:0xc000
	s_waitcnt lgkmcnt(7)
	v_mfma_f32_32x32x16_bf16 v[64:79], v[148:151], v[124:127], v[64:79]
	ds_read_b128 v[148:151], v186 offset:0xe000
	s_waitcnt lgkmcnt(7)
	v_mfma_f32_32x32x16_bf16 v[80:95], v[196:199], v[120:123], v[80:95]
	s_waitcnt lgkmcnt(6)
	v_mfma_f32_32x32x16_bf16 v[64:79], v[200:203], v[120:123], v[64:79]
	s_waitcnt lgkmcnt(5)
	v_mfma_f32_32x32x16_bf16 v[80:95], v[204:207], v[116:119], v[80:95]
	s_waitcnt lgkmcnt(4)
	v_mfma_f32_32x32x16_bf16 v[64:79], v[208:211], v[116:119], v[64:79]
	s_waitcnt lgkmcnt(3)
	v_mfma_f32_32x32x16_bf16 v[80:95], v[160:163], v[140:143], v[80:95]
	s_waitcnt lgkmcnt(2)
	v_mfma_f32_32x32x16_bf16 v[64:79], v[156:159], v[140:143], v[64:79]
	s_waitcnt lgkmcnt(1)
	v_mfma_f32_32x32x16_bf16 v[80:95], v[152:155], v[132:135], v[80:95]
	s_waitcnt lgkmcnt(0)
	v_mfma_f32_32x32x16_bf16 v[64:79], v[148:151], v[132:135], v[64:79]
	s_setprio 0
	s_waitcnt lgkmcnt(0)
	s_barrier
	s_cmp_le_i32 s0, s78
	s_mov_b64 s[0:1], -1
	s_cbranch_scc0 .LBB0_1332
	s_add_i32 s0, s84, 0x7f
	s_cmp_le_i32 s0, s75
	s_cbranch_scc1 .LBB0_1331
	v_subrev_u32_e32 v97, 64, v193
	v_cmp_gt_i32_e64 s[58:59], 26, v97
	v_cmp_gt_i32_e64 s[60:61], 27, v97
	v_cmp_gt_i32_e64 s[56:57], 25, v97
	v_cmp_gt_i32_e64 s[54:55], 24, v97
	v_cmp_gt_i32_e64 s[52:53], 19, v97
	v_cmp_gt_i32_e64 s[50:51], 18, v97
	v_cmp_gt_i32_e64 s[48:49], 17, v97
	v_cmp_gt_i32_e64 s[46:47], 16, v97
	v_cmp_gt_i32_e64 s[44:45], 11, v97
	v_cmp_gt_i32_e64 s[42:43], 10, v97
	v_cmp_gt_i32_e64 s[40:41], 9, v97
	v_cmp_gt_i32_e64 s[38:39], 8, v97
	v_cmp_gt_i32_e64 s[36:37], 3, v97
	v_cmp_gt_i32_e64 s[34:35], 2, v97
	v_cmp_gt_i32_e64 s[30:31], 1, v97
	v_cmp_gt_i32_e64 s[28:29], 0, v97
	v_cmp_gt_i32_e64 s[26:27], 58, v97
	v_cndmask_b32_e64 v80, v80, v169, s[28:29]
	v_cmp_gt_i32_e64 s[28:29], 59, v97
	v_cmp_gt_i32_e64 s[24:25], 57, v97
	v_cmp_gt_i32_e64 s[22:23], 56, v97
	v_cmp_gt_i32_e64 s[20:21], 51, v97
	v_cmp_gt_i32_e64 s[18:19], 50, v97
	v_cmp_gt_i32_e64 s[16:17], 49, v97
	v_cmp_gt_i32_e64 s[14:15], 48, v97
	v_cmp_gt_i32_e64 s[12:13], 43, v97
	v_cmp_gt_i32_e64 s[10:11], 42, v97
	v_cmp_gt_i32_e64 s[8:9], 41, v97
	v_cmp_gt_i32_e64 s[6:7], 40, v97
	v_cmp_gt_i32_e64 s[4:5], 35, v97
	v_cmp_gt_i32_e64 s[2:3], 34, v97
	v_cmp_gt_i32_e64 s[0:1], 33, v97
	v_cmp_gt_i32_e32 vcc, 32, v97
	v_cndmask_b32_e64 v95, v95, v169, s[60:61]
	v_cndmask_b32_e64 v94, v94, v169, s[58:59]
	v_cndmask_b32_e64 v93, v93, v169, s[56:57]
	v_cndmask_b32_e64 v92, v92, v169, s[54:55]
	v_cndmask_b32_e64 v91, v91, v169, s[52:53]
	v_cndmask_b32_e64 v90, v90, v169, s[50:51]
	v_cndmask_b32_e64 v89, v89, v169, s[48:49]
	v_cndmask_b32_e64 v88, v88, v169, s[46:47]
	v_cndmask_b32_e64 v87, v87, v169, s[44:45]
	v_cndmask_b32_e64 v86, v86, v169, s[42:43]
	v_cndmask_b32_e64 v85, v85, v169, s[40:41]
	v_cndmask_b32_e64 v84, v84, v169, s[38:39]
	v_cndmask_b32_e64 v83, v83, v169, s[36:37]
	v_cndmask_b32_e64 v82, v82, v169, s[34:35]
	v_cndmask_b32_e64 v81, v81, v169, s[30:31]
	v_cndmask_b32_e64 v79, v79, v169, s[28:29]
	v_cndmask_b32_e64 v78, v78, v169, s[26:27]
	v_cndmask_b32_e64 v77, v77, v169, s[24:25]
	v_cndmask_b32_e64 v76, v76, v169, s[22:23]
	v_cndmask_b32_e64 v75, v75, v169, s[20:21]
	v_cndmask_b32_e64 v74, v74, v169, s[18:19]
	v_cndmask_b32_e64 v73, v73, v169, s[16:17]
	v_cndmask_b32_e64 v72, v72, v169, s[14:15]
	v_cndmask_b32_e64 v71, v71, v169, s[12:13]
	v_cndmask_b32_e64 v70, v70, v169, s[10:11]
	v_cndmask_b32_e64 v69, v69, v169, s[8:9]
	v_cndmask_b32_e64 v68, v68, v169, s[6:7]
	v_cndmask_b32_e64 v67, v67, v169, s[4:5]
	v_cndmask_b32_e64 v66, v66, v169, s[2:3]
	v_cndmask_b32_e64 v65, v65, v169, s[0:1]
	v_cndmask_b32_e32 v64, v64, v169, vcc

.LBB0_1336:
	v_lshl_add_u64 v[64:65], s[0:1], 0, v[164:165]
	v_lshl_add_u64 v[66:67], s[0:1], 0, v[166:167]
	global_load_dwordx4 v[100:103], v[64:65], off
	global_load_dwordx4 v[104:107], v[66:67], off
	v_lshl_add_u64 v[66:67], s[2:3], 0, v[164:165]
	v_lshl_add_u64 v[64:65], s[2:3], 0, v[166:167]
	global_load_dwordx4 v[112:115], v[66:67], off
	global_load_dwordx4 v[108:111], v[64:65], off
	s_waitcnt lgkmcnt(0)
	s_barrier
	s_setprio 1
	ds_read_b128 v[64:67], v194
	ds_read_b128 v[68:71], v194 offset:32
	ds_read_b128 v[72:75], v194 offset:64
	ds_read_b128 v[76:79], v194 offset:96
	ds_read_b128 v[196:199], v194 offset:128
	ds_read_b128 v[200:203], v194 offset:160
	ds_read_b128 v[204:207], v194 offset:192
	ds_read_b128 v[208:211], v194 offset:224
	s_waitcnt lgkmcnt(4)
	v_pk_add_f32 v[94:95], v[78:79], v[180:181] op_sel:[0,1] op_sel_hi:[1,1] neg_lo:[0,1] neg_hi:[0,1]
	v_pk_add_f32 v[92:93], v[76:77], v[180:181] op_sel:[0,1] op_sel_hi:[1,1] neg_lo:[0,1] neg_hi:[0,1]
	v_pk_add_f32 v[90:91], v[74:75], v[180:181] op_sel:[0,1] op_sel_hi:[1,1] neg_lo:[0,1] neg_hi:[0,1]
	v_pk_add_f32 v[88:89], v[72:73], v[180:181] op_sel:[0,1] op_sel_hi:[1,1] neg_lo:[0,1] neg_hi:[0,1]
	v_pk_add_f32 v[86:87], v[70:71], v[180:181] op_sel:[0,1] op_sel_hi:[1,1] neg_lo:[0,1] neg_hi:[0,1]
	v_pk_add_f32 v[84:85], v[68:69], v[180:181] op_sel:[0,1] op_sel_hi:[1,1] neg_lo:[0,1] neg_hi:[0,1]
	v_pk_add_f32 v[82:83], v[66:67], v[180:181] op_sel:[0,1] op_sel_hi:[1,1] neg_lo:[0,1] neg_hi:[0,1]
	v_pk_add_f32 v[80:81], v[64:65], v[180:181] op_sel:[0,1] op_sel_hi:[1,1] neg_lo:[0,1] neg_hi:[0,1]
	s_waitcnt lgkmcnt(0)
	v_pk_add_f32 v[78:79], v[210:211], v[180:181] op_sel:[0,1] op_sel_hi:[1,1] neg_lo:[0,1] neg_hi:[0,1]
	v_pk_add_f32 v[76:77], v[208:209], v[180:181] op_sel:[0,1] op_sel_hi:[1,1] neg_lo:[0,1] neg_hi:[0,1]
	v_pk_add_f32 v[74:75], v[206:207], v[180:181] op_sel:[0,1] op_sel_hi:[1,1] neg_lo:[0,1] neg_hi:[0,1]
	v_pk_add_f32 v[72:73], v[204:205], v[180:181] op_sel:[0,1] op_sel_hi:[1,1] neg_lo:[0,1] neg_hi:[0,1]
	v_pk_add_f32 v[70:71], v[202:203], v[180:181] op_sel:[0,1] op_sel_hi:[1,1] neg_lo:[0,1] neg_hi:[0,1]
	v_pk_add_f32 v[68:69], v[200:201], v[180:181] op_sel:[0,1] op_sel_hi:[1,1] neg_lo:[0,1] neg_hi:[0,1]
	v_pk_add_f32 v[66:67], v[198:199], v[180:181] op_sel:[0,1] op_sel_hi:[1,1] neg_lo:[0,1] neg_hi:[0,1]
	v_pk_add_f32 v[64:65], v[196:197], v[180:181] op_sel:[0,1] op_sel_hi:[1,1] neg_lo:[0,1] neg_hi:[0,1]
	ds_read_b64_tr_b16 v[196:197], v179 offset:0x4000
	ds_read_b64_tr_b16 v[198:199], v179 offset:0x4800
	ds_read_b64_tr_b16 v[200:201], v179 offset:0x5000
	ds_read_b64_tr_b16 v[202:203], v179 offset:0x5800
	ds_read_b64_tr_b16 v[204:205], v179 offset:0x6000
	ds_read_b64_tr_b16 v[206:207], v179 offset:0x6800
	ds_read_b64_tr_b16 v[208:209], v179 offset:0x7000
	ds_read_b64_tr_b16 v[210:211], v179 offset:0x7800
	ds_read_b64_tr_b16 v[212:213], v179 offset:0x4200
	ds_read_b64_tr_b16 v[214:215], v179 offset:0x4a00
	ds_read_b64_tr_b16 v[216:217], v179 offset:0x5200
	ds_read_b64_tr_b16 v[218:219], v179 offset:0x5a00
	ds_read_b64_tr_b16 v[220:221], v179 offset:0x6200
	ds_read_b64_tr_b16 v[222:223], v179 offset:0x6a00
	ds_read_b64_tr_b16 v[224:225], v179 offset:0x7200
	ds_read_b64_tr_b16 v[226:227], v179 offset:0x7a00
	s_waitcnt lgkmcnt(14)
	s_nop 0
	v_mfma_f32_32x32x16_bf16 v[0:15], v[160:163], v[196:199], v[0:15]
	ds_read_b64_tr_b16 v[196:197], v179 offset:0x4400
	ds_read_b64_tr_b16 v[198:199], v179 offset:0x4c00
	s_waitcnt lgkmcnt(14)
	v_mfma_f32_32x32x16_bf16 v[0:15], v[156:159], v[200:203], v[0:15]
	ds_read_b64_tr_b16 v[200:201], v179 offset:0x5400
	ds_read_b64_tr_b16 v[202:203], v179 offset:0x5c00
	s_waitcnt lgkmcnt(14)
	v_mfma_f32_32x32x16_bf16 v[0:15], v[152:155], v[204:207], v[0:15]
	ds_read_b64_tr_b16 v[204:205], v179 offset:0x6400
	ds_read_b64_tr_b16 v[206:207], v179 offset:0x6c00
	s_waitcnt lgkmcnt(14)
	v_mfma_f32_32x32x16_bf16 v[0:15], v[148:151], v[208:211], v[0:15]
	ds_read_b64_tr_b16 v[208:209], v179 offset:0x7400
	ds_read_b64_tr_b16 v[210:211], v179 offset:0x7c00
	s_waitcnt lgkmcnt(14)
	v_mfma_f32_32x32x16_bf16 v[48:63], v[160:163], v[212:215], v[48:63]
	ds_read_b64_tr_b16 v[212:213], v179 offset:0x4600
	ds_read_b64_tr_b16 v[214:215], v179 offset:0x4e00
	s_waitcnt lgkmcnt(14)
	v_mfma_f32_32x32x16_bf16 v[48:63], v[156:159], v[216:219], v[48:63]
	ds_read_b64_tr_b16 v[216:217], v179 offset:0x5600
	ds_read_b64_tr_b16 v[218:219], v179 offset:0x5e00
	s_waitcnt lgkmcnt(14)
	v_mfma_f32_32x32x16_bf16 v[48:63], v[152:155], v[220:223], v[48:63]
	ds_read_b64_tr_b16 v[220:221], v179 offset:0x6600
	ds_read_b64_tr_b16 v[222:223], v179 offset:0x6e00
	s_waitcnt lgkmcnt(14)
	v_mfma_f32_32x32x16_bf16 v[48:63], v[148:151], v[224:227], v[48:63]
	ds_read_b64_tr_b16 v[224:225], v179 offset:0x7600
	ds_read_b64_tr_b16 v[226:227], v179 offset:0x7e00
	s_waitcnt lgkmcnt(14)
	v_mfma_f32_32x32x16_bf16 v[32:47], v[160:163], v[196:199], v[32:47]
	ds_read_b128 v[196:199], v189 offset:0x8000
	s_waitcnt lgkmcnt(13)
	v_mfma_f32_32x32x16_bf16 v[32:47], v[156:159], v[200:203], v[32:47]
	ds_read_b128 v[200:203], v189 offset:0xa000
	s_waitcnt lgkmcnt(12)
	v_mfma_f32_32x32x16_bf16 v[32:47], v[152:155], v[204:207], v[32:47]
	ds_read_b128 v[204:207], v188 offset:0x8000
	s_waitcnt lgkmcnt(11)
	v_mfma_f32_32x32x16_bf16 v[32:47], v[148:151], v[208:211], v[32:47]
	ds_read_b128 v[208:211], v188 offset:0xa000
	s_waitcnt lgkmcnt(10)
	v_mfma_f32_32x32x16_bf16 v[16:31], v[160:163], v[212:215], v[16:31]
	ds_read_b128 v[160:163], v187 offset:0x8000
	s_waitcnt lgkmcnt(9)
	v_mfma_f32_32x32x16_bf16 v[16:31], v[156:159], v[216:219], v[16:31]
	ds_read_b128 v[156:159], v187 offset:0xa000
	s_waitcnt lgkmcnt(8)
	v_mfma_f32_32x32x16_bf16 v[16:31], v[152:155], v[220:223], v[16:31]
	ds_read_b128 v[152:155], v184 offset:0x8000
	s_waitcnt lgkmcnt(7)
	v_mfma_f32_32x32x16_bf16 v[16:31], v[148:151], v[224:227], v[16:31]
	ds_read_b128 v[148:151], v184 offset:0xa000
	s_waitcnt lgkmcnt(7)
	v_mfma_f32_32x32x16_bf16 v[80:95], v[196:199], v[144:147], v[80:95]
	ds_read_b128 v[196:199], v182 offset:0x8000
	s_waitcnt lgkmcnt(7)
	v_mfma_f32_32x32x16_bf16 v[64:79], v[200:203], v[144:147], v[64:79]
	ds_read_b128 v[200:203], v182 offset:0xa000
	s_waitcnt lgkmcnt(7)
	v_mfma_f32_32x32x16_bf16 v[80:95], v[204:207], v[136:139], v[80:95]
	ds_read_b128 v[204:207], v183 offset:0x8000
	s_waitcnt lgkmcnt(7)
	v_mfma_f32_32x32x16_bf16 v[64:79], v[208:211], v[136:139], v[64:79]
	ds_read_b128 v[208:211], v183 offset:0xa000
	s_waitcnt lgkmcnt(7)
	v_mfma_f32_32x32x16_bf16 v[80:95], v[160:163], v[128:131], v[80:95]
	ds_read_b128 v[160:163], v185 offset:0x8000
	s_waitcnt lgkmcnt(7)
	v_mfma_f32_32x32x16_bf16 v[64:79], v[156:159], v[128:131], v[64:79]
	ds_read_b128 v[156:159], v185 offset:0xa000
	s_waitcnt lgkmcnt(7)
	v_mfma_f32_32x32x16_bf16 v[80:95], v[152:155], v[124:127], v[80:95]
	ds_read_b128 v[152:155], v186 offset:0x8000
	s_waitcnt lgkmcnt(7)
	v_mfma_f32_32x32x16_bf16 v[64:79], v[148:151], v[124:127], v[64:79]
	ds_read_b128 v[148:151], v186 offset:0xa000
	s_waitcnt lgkmcnt(7)
	v_mfma_f32_32x32x16_bf16 v[80:95], v[196:199], v[120:123], v[80:95]
	s_waitcnt lgkmcnt(6)
	v_mfma_f32_32x32x16_bf16 v[64:79], v[200:203], v[120:123], v[64:79]
	s_waitcnt lgkmcnt(5)
	v_mfma_f32_32x32x16_bf16 v[80:95], v[204:207], v[116:119], v[80:95]
	s_waitcnt lgkmcnt(4)
	v_mfma_f32_32x32x16_bf16 v[64:79], v[208:211], v[116:119], v[64:79]
	s_waitcnt lgkmcnt(3)
	v_mfma_f32_32x32x16_bf16 v[80:95], v[160:163], v[140:143], v[80:95]
	s_waitcnt lgkmcnt(2)
	v_mfma_f32_32x32x16_bf16 v[64:79], v[156:159], v[140:143], v[64:79]
	s_waitcnt lgkmcnt(1)
	v_mfma_f32_32x32x16_bf16 v[80:95], v[152:155], v[132:135], v[80:95]
	s_waitcnt lgkmcnt(0)
	v_mfma_f32_32x32x16_bf16 v[64:79], v[148:151], v[132:135], v[64:79]
	s_setprio 0
	s_waitcnt lgkmcnt(0)
	s_barrier
	s_cmp_le_i32 s84, s78
	s_mov_b64 s[0:1], -1
	s_cbranch_scc0 .LBB0_1340
	s_add_i32 s0, s84, 63
	s_cmp_le_i32 s0, s75
	s_cbranch_scc1 .LBB0_1339
	v_cmp_gt_i32_e64 s[58:59], 26, v193
	v_cmp_gt_i32_e64 s[60:61], 27, v193
	v_cmp_gt_i32_e64 s[56:57], 25, v193
	v_cmp_gt_i32_e64 s[54:55], 24, v193
	v_cmp_gt_i32_e64 s[52:53], 19, v193
	v_cmp_gt_i32_e64 s[50:51], 18, v193
	v_cmp_gt_i32_e64 s[48:49], 17, v193
	v_cmp_gt_i32_e64 s[46:47], 16, v193
	v_cmp_gt_i32_e64 s[44:45], 11, v193
	v_cmp_gt_i32_e64 s[42:43], 10, v193
	v_cmp_gt_i32_e64 s[40:41], 9, v193
	v_cmp_gt_i32_e64 s[38:39], 8, v193
	v_cmp_gt_i32_e64 s[36:37], 3, v193
	v_cmp_gt_i32_e64 s[34:35], 2, v193
	v_cmp_gt_i32_e64 s[30:31], 1, v193
	v_cmp_gt_i32_e64 s[28:29], 0, v193
	v_cmp_gt_i32_e64 s[26:27], 58, v193
	v_cndmask_b32_e64 v80, v80, v169, s[28:29]
	v_cmp_gt_i32_e64 s[28:29], 59, v193
	v_cmp_gt_i32_e64 s[24:25], 57, v193
	v_cmp_gt_i32_e64 s[22:23], 56, v193
	v_cmp_gt_i32_e64 s[20:21], 51, v193
	v_cmp_gt_i32_e64 s[18:19], 50, v193
	v_cmp_gt_i32_e64 s[16:17], 49, v193
	v_cmp_gt_i32_e64 s[14:15], 48, v193
	v_cmp_gt_i32_e64 s[12:13], 43, v193
	v_cmp_gt_i32_e64 s[10:11], 42, v193
	v_cmp_gt_i32_e64 s[8:9], 41, v193
	v_cmp_gt_i32_e64 s[6:7], 40, v193
	v_cmp_gt_i32_e64 s[4:5], 35, v193
	v_cmp_gt_i32_e64 s[2:3], 34, v193
	v_cmp_gt_i32_e64 s[0:1], 33, v193
	v_cmp_gt_i32_e32 vcc, 32, v193
	v_cndmask_b32_e64 v95, v95, v169, s[60:61]
	v_cndmask_b32_e64 v94, v94, v169, s[58:59]
	v_cndmask_b32_e64 v93, v93, v169, s[56:57]
	v_cndmask_b32_e64 v92, v92, v169, s[54:55]
	v_cndmask_b32_e64 v91, v91, v169, s[52:53]
	v_cndmask_b32_e64 v90, v90, v169, s[50:51]
	v_cndmask_b32_e64 v89, v89, v169, s[48:49]
	v_cndmask_b32_e64 v88, v88, v169, s[46:47]
	v_cndmask_b32_e64 v87, v87, v169, s[44:45]
	v_cndmask_b32_e64 v86, v86, v169, s[42:43]
	v_cndmask_b32_e64 v85, v85, v169, s[40:41]
	v_cndmask_b32_e64 v84, v84, v169, s[38:39]
	v_cndmask_b32_e64 v83, v83, v169, s[36:37]
	v_cndmask_b32_e64 v82, v82, v169, s[34:35]
	v_cndmask_b32_e64 v81, v81, v169, s[30:31]
	v_cndmask_b32_e64 v79, v79, v169, s[28:29]
	v_cndmask_b32_e64 v78, v78, v169, s[26:27]
	v_cndmask_b32_e64 v77, v77, v169, s[24:25]
	v_cndmask_b32_e64 v76, v76, v169, s[22:23]
	v_cndmask_b32_e64 v75, v75, v169, s[20:21]
	v_cndmask_b32_e64 v74, v74, v169, s[18:19]
	v_cndmask_b32_e64 v73, v73, v169, s[16:17]
	v_cndmask_b32_e64 v72, v72, v169, s[14:15]
	v_cndmask_b32_e64 v71, v71, v169, s[12:13]
	v_cndmask_b32_e64 v70, v70, v169, s[10:11]
	v_cndmask_b32_e64 v69, v69, v169, s[8:9]
	v_cndmask_b32_e64 v68, v68, v169, s[6:7]
	v_cndmask_b32_e64 v67, v67, v169, s[4:5]
	v_cndmask_b32_e64 v66, v66, v169, s[2:3]
	v_cndmask_b32_e64 v65, v65, v169, s[0:1]
	v_cndmask_b32_e32 v64, v64, v169, vcc

.LBB0_1350:
	s_setprio 1
	v_lshl_add_u32 v80, s82, 8, v190
	ds_read_b128 v[64:67], v80
	ds_read_b128 v[68:71], v80 offset:32
	ds_read_b128 v[72:75], v80 offset:64
	ds_read_b128 v[76:79], v80 offset:96
	ds_read_b128 v[192:195], v80 offset:128
	ds_read_b128 v[196:199], v80 offset:160
	ds_read_b128 v[200:203], v80 offset:192
	ds_read_b128 v[204:207], v80 offset:224
	s_lshl_b32 s2, s82, 6
	s_waitcnt lgkmcnt(4)
	v_pk_add_f32 v[94:95], v[78:79], v[180:181] op_sel:[0,1] op_sel_hi:[1,1] neg_lo:[0,1] neg_hi:[0,1]
	v_pk_add_f32 v[92:93], v[76:77], v[180:181] op_sel:[0,1] op_sel_hi:[1,1] neg_lo:[0,1] neg_hi:[0,1]
	v_pk_add_f32 v[90:91], v[74:75], v[180:181] op_sel:[0,1] op_sel_hi:[1,1] neg_lo:[0,1] neg_hi:[0,1]
	v_pk_add_f32 v[88:89], v[72:73], v[180:181] op_sel:[0,1] op_sel_hi:[1,1] neg_lo:[0,1] neg_hi:[0,1]
	v_pk_add_f32 v[86:87], v[70:71], v[180:181] op_sel:[0,1] op_sel_hi:[1,1] neg_lo:[0,1] neg_hi:[0,1]
	v_pk_add_f32 v[84:85], v[68:69], v[180:181] op_sel:[0,1] op_sel_hi:[1,1] neg_lo:[0,1] neg_hi:[0,1]
	v_pk_add_f32 v[82:83], v[66:67], v[180:181] op_sel:[0,1] op_sel_hi:[1,1] neg_lo:[0,1] neg_hi:[0,1]
	v_pk_add_f32 v[80:81], v[64:65], v[180:181] op_sel:[0,1] op_sel_hi:[1,1] neg_lo:[0,1] neg_hi:[0,1]
	s_waitcnt lgkmcnt(0)
	v_pk_add_f32 v[78:79], v[206:207], v[180:181] op_sel:[0,1] op_sel_hi:[1,1] neg_lo:[0,1] neg_hi:[0,1]
	v_pk_add_f32 v[76:77], v[204:205], v[180:181] op_sel:[0,1] op_sel_hi:[1,1] neg_lo:[0,1] neg_hi:[0,1]
	v_pk_add_f32 v[74:75], v[202:203], v[180:181] op_sel:[0,1] op_sel_hi:[1,1] neg_lo:[0,1] neg_hi:[0,1]
	v_pk_add_f32 v[72:73], v[200:201], v[180:181] op_sel:[0,1] op_sel_hi:[1,1] neg_lo:[0,1] neg_hi:[0,1]
	v_pk_add_f32 v[70:71], v[198:199], v[180:181] op_sel:[0,1] op_sel_hi:[1,1] neg_lo:[0,1] neg_hi:[0,1]
	v_pk_add_f32 v[68:69], v[196:197], v[180:181] op_sel:[0,1] op_sel_hi:[1,1] neg_lo:[0,1] neg_hi:[0,1]
	v_pk_add_f32 v[66:67], v[194:195], v[180:181] op_sel:[0,1] op_sel_hi:[1,1] neg_lo:[0,1] neg_hi:[0,1]
	v_pk_add_f32 v[64:65], v[192:193], v[180:181] op_sel:[0,1] op_sel_hi:[1,1] neg_lo:[0,1] neg_hi:[0,1]
	ds_read_b64_tr_b16 v[192:193], v179 offset:0
	ds_read_b64_tr_b16 v[194:195], v179 offset:0x800
	ds_read_b64_tr_b16 v[196:197], v179 offset:0x1000
	ds_read_b64_tr_b16 v[198:199], v179 offset:0x1800
	ds_read_b64_tr_b16 v[200:201], v179 offset:0x2000
	ds_read_b64_tr_b16 v[202:203], v179 offset:0x2800
	ds_read_b64_tr_b16 v[204:205], v179 offset:0x3000
	ds_read_b64_tr_b16 v[206:207], v179 offset:0x3800
	ds_read_b64_tr_b16 v[208:209], v179 offset:0x200
	ds_read_b64_tr_b16 v[210:211], v179 offset:0xa00
	ds_read_b64_tr_b16 v[212:213], v179 offset:0x1200
	ds_read_b64_tr_b16 v[214:215], v179 offset:0x1a00
	ds_read_b64_tr_b16 v[216:217], v179 offset:0x2200
	ds_read_b64_tr_b16 v[218:219], v179 offset:0x2a00
	ds_read_b64_tr_b16 v[220:221], v179 offset:0x3200
	ds_read_b64_tr_b16 v[222:223], v179 offset:0x3a00
	s_waitcnt lgkmcnt(14)
	s_nop 0
	v_mfma_f32_32x32x16_bf16 v[0:15], v[160:163], v[192:195], v[0:15]
	ds_read_b64_tr_b16 v[192:193], v179 offset:0x400
	ds_read_b64_tr_b16 v[194:195], v179 offset:0xc00
	s_waitcnt lgkmcnt(14)
	v_mfma_f32_32x32x16_bf16 v[0:15], v[156:159], v[196:199], v[0:15]
	ds_read_b64_tr_b16 v[196:197], v179 offset:0x1400
	ds_read_b64_tr_b16 v[198:199], v179 offset:0x1c00
	s_waitcnt lgkmcnt(14)
	v_mfma_f32_32x32x16_bf16 v[0:15], v[152:155], v[200:203], v[0:15]
	ds_read_b64_tr_b16 v[200:201], v179 offset:0x2400
	ds_read_b64_tr_b16 v[202:203], v179 offset:0x2c00
	s_waitcnt lgkmcnt(14)
	v_mfma_f32_32x32x16_bf16 v[0:15], v[148:151], v[204:207], v[0:15]
	ds_read_b64_tr_b16 v[204:205], v179 offset:0x3400
	ds_read_b64_tr_b16 v[206:207], v179 offset:0x3c00
	s_waitcnt lgkmcnt(14)
	v_mfma_f32_32x32x16_bf16 v[48:63], v[160:163], v[208:211], v[48:63]
	ds_read_b64_tr_b16 v[208:209], v179 offset:0x600
	ds_read_b64_tr_b16 v[210:211], v179 offset:0xe00
	s_waitcnt lgkmcnt(14)
	v_mfma_f32_32x32x16_bf16 v[48:63], v[156:159], v[212:215], v[48:63]
	ds_read_b64_tr_b16 v[212:213], v179 offset:0x1600
	ds_read_b64_tr_b16 v[214:215], v179 offset:0x1e00
	s_waitcnt lgkmcnt(14)
	v_mfma_f32_32x32x16_bf16 v[48:63], v[152:155], v[216:219], v[48:63]
	ds_read_b64_tr_b16 v[216:217], v179 offset:0x2600
	ds_read_b64_tr_b16 v[218:219], v179 offset:0x2e00
	s_waitcnt lgkmcnt(14)
	v_mfma_f32_32x32x16_bf16 v[48:63], v[148:151], v[220:223], v[48:63]
	ds_read_b64_tr_b16 v[220:221], v179 offset:0x3600
	ds_read_b64_tr_b16 v[222:223], v179 offset:0x3e00
	s_waitcnt lgkmcnt(14)
	v_mfma_f32_32x32x16_bf16 v[32:47], v[160:163], v[192:195], v[32:47]
	ds_read_b128 v[192:195], v189 offset:0xc000
	s_waitcnt lgkmcnt(13)
	v_mfma_f32_32x32x16_bf16 v[32:47], v[156:159], v[196:199], v[32:47]
	ds_read_b128 v[196:199], v189 offset:0xe000
	s_waitcnt lgkmcnt(12)
	v_mfma_f32_32x32x16_bf16 v[32:47], v[152:155], v[200:203], v[32:47]
	ds_read_b128 v[200:203], v188 offset:0xc000
	s_waitcnt lgkmcnt(11)
	v_mfma_f32_32x32x16_bf16 v[32:47], v[148:151], v[204:207], v[32:47]
	ds_read_b128 v[204:207], v188 offset:0xe000
	s_waitcnt lgkmcnt(10)
	v_mfma_f32_32x32x16_bf16 v[16:31], v[160:163], v[208:211], v[16:31]
	ds_read_b128 v[160:163], v187 offset:0xc000
	s_waitcnt lgkmcnt(9)
	v_mfma_f32_32x32x16_bf16 v[16:31], v[156:159], v[212:215], v[16:31]
	ds_read_b128 v[156:159], v187 offset:0xe000
	s_waitcnt lgkmcnt(8)
	v_mfma_f32_32x32x16_bf16 v[16:31], v[152:155], v[216:219], v[16:31]
	ds_read_b128 v[152:155], v184 offset:0xc000
	s_waitcnt lgkmcnt(7)
	v_mfma_f32_32x32x16_bf16 v[16:31], v[148:151], v[220:223], v[16:31]
	ds_read_b128 v[148:151], v184 offset:0xe000
	s_waitcnt lgkmcnt(7)
	v_mfma_f32_32x32x16_bf16 v[80:95], v[192:195], v[144:147], v[80:95]
	ds_read_b128 v[192:195], v182 offset:0xc000
	s_waitcnt lgkmcnt(7)
	v_mfma_f32_32x32x16_bf16 v[64:79], v[196:199], v[144:147], v[64:79]
	ds_read_b128 v[144:147], v182 offset:0xe000
	s_waitcnt lgkmcnt(7)
	v_mfma_f32_32x32x16_bf16 v[80:95], v[200:203], v[136:139], v[80:95]
	ds_read_b128 v[196:199], v183 offset:0xc000
	s_waitcnt lgkmcnt(7)
	v_mfma_f32_32x32x16_bf16 v[64:79], v[204:207], v[136:139], v[64:79]
	ds_read_b128 v[136:139], v183 offset:0xe000
	s_waitcnt lgkmcnt(7)
	v_mfma_f32_32x32x16_bf16 v[80:95], v[160:163], v[128:131], v[80:95]
	ds_read_b128 v[160:163], v185 offset:0xc000
	s_waitcnt lgkmcnt(7)
	v_mfma_f32_32x32x16_bf16 v[64:79], v[156:159], v[128:131], v[64:79]
	ds_read_b128 v[128:131], v185 offset:0xe000
	s_waitcnt lgkmcnt(7)
	v_mfma_f32_32x32x16_bf16 v[80:95], v[152:155], v[124:127], v[80:95]
	ds_read_b128 v[152:155], v186 offset:0xc000
	s_waitcnt lgkmcnt(7)
	v_mfma_f32_32x32x16_bf16 v[64:79], v[148:151], v[124:127], v[64:79]
	ds_read_b128 v[124:127], v186 offset:0xe000
	s_waitcnt lgkmcnt(7)
	v_mfma_f32_32x32x16_bf16 v[80:95], v[192:195], v[120:123], v[80:95]
	s_waitcnt lgkmcnt(6)
	v_mfma_f32_32x32x16_bf16 v[64:79], v[144:147], v[120:123], v[64:79]
	s_waitcnt lgkmcnt(5)
	v_mfma_f32_32x32x16_bf16 v[80:95], v[196:199], v[116:119], v[80:95]
	s_waitcnt lgkmcnt(4)
	v_mfma_f32_32x32x16_bf16 v[64:79], v[136:139], v[116:119], v[64:79]
	s_waitcnt lgkmcnt(3)
	v_mfma_f32_32x32x16_bf16 v[80:95], v[160:163], v[140:143], v[80:95]
	s_waitcnt lgkmcnt(2)
	v_mfma_f32_32x32x16_bf16 v[64:79], v[128:131], v[140:143], v[64:79]
	s_waitcnt lgkmcnt(1)
	v_mfma_f32_32x32x16_bf16 v[80:95], v[152:155], v[132:135], v[80:95]
	s_waitcnt lgkmcnt(0)
	v_mfma_f32_32x32x16_bf16 v[64:79], v[124:127], v[132:135], v[64:79]
	s_setprio 0
	s_waitcnt lgkmcnt(0)
	s_barrier
	s_cmp_le_i32 s2, s78
	s_mov_b64 s[0:1], -1
	s_cbranch_scc0 .LBB0_1354
	s_or_b32 s0, s2, 63
	s_cmp_le_i32 s0, s75
	s_cbranch_scc1 .LBB0_1353
	v_subrev_u32_e32 v97, s2, v178
	v_cmp_gt_i32_e64 s[58:59], 26, v97
	v_cmp_gt_i32_e64 s[60:61], 27, v97
	v_cmp_gt_i32_e64 s[56:57], 25, v97
	v_cmp_gt_i32_e64 s[54:55], 24, v97
	v_cmp_gt_i32_e64 s[52:53], 19, v97
	v_cmp_gt_i32_e64 s[50:51], 18, v97
	v_cmp_gt_i32_e64 s[48:49], 17, v97
	v_cmp_gt_i32_e64 s[46:47], 16, v97
	v_cmp_gt_i32_e64 s[44:45], 11, v97
	v_cmp_gt_i32_e64 s[42:43], 10, v97
	v_cmp_gt_i32_e64 s[40:41], 9, v97
	v_cmp_gt_i32_e64 s[38:39], 8, v97
	v_cmp_gt_i32_e64 s[36:37], 3, v97
	v_cmp_gt_i32_e64 s[34:35], 2, v97
	v_cmp_gt_i32_e64 s[30:31], 1, v97
	v_cmp_gt_i32_e64 s[28:29], 0, v97
	v_cmp_gt_i32_e64 s[26:27], 58, v97
	v_cndmask_b32_e64 v80, v80, v169, s[28:29]
	v_cmp_gt_i32_e64 s[28:29], 59, v97
	v_cmp_gt_i32_e64 s[24:25], 57, v97
	v_cmp_gt_i32_e64 s[22:23], 56, v97
	v_cmp_gt_i32_e64 s[20:21], 51, v97
	v_cmp_gt_i32_e64 s[18:19], 50, v97
	v_cmp_gt_i32_e64 s[16:17], 49, v97
	v_cmp_gt_i32_e64 s[14:15], 48, v97
	v_cmp_gt_i32_e64 s[12:13], 43, v97
	v_cmp_gt_i32_e64 s[10:11], 42, v97
	v_cmp_gt_i32_e64 s[8:9], 41, v97
	v_cmp_gt_i32_e64 s[6:7], 40, v97
	v_cmp_gt_i32_e64 s[4:5], 35, v97
	v_cmp_gt_i32_e64 s[2:3], 34, v97
	v_cmp_gt_i32_e64 s[0:1], 33, v97
	v_cmp_gt_i32_e32 vcc, 32, v97
	v_cndmask_b32_e64 v95, v95, v169, s[60:61]
	v_cndmask_b32_e64 v94, v94, v169, s[58:59]
	v_cndmask_b32_e64 v93, v93, v169, s[56:57]
	v_cndmask_b32_e64 v92, v92, v169, s[54:55]
	v_cndmask_b32_e64 v91, v91, v169, s[52:53]
	v_cndmask_b32_e64 v90, v90, v169, s[50:51]
	v_cndmask_b32_e64 v89, v89, v169, s[48:49]
	v_cndmask_b32_e64 v88, v88, v169, s[46:47]
	v_cndmask_b32_e64 v87, v87, v169, s[44:45]
	v_cndmask_b32_e64 v86, v86, v169, s[42:43]
	v_cndmask_b32_e64 v85, v85, v169, s[40:41]
	v_cndmask_b32_e64 v84, v84, v169, s[38:39]
	v_cndmask_b32_e64 v83, v83, v169, s[36:37]
	v_cndmask_b32_e64 v82, v82, v169, s[34:35]
	v_cndmask_b32_e64 v81, v81, v169, s[30:31]
	v_cndmask_b32_e64 v79, v79, v169, s[28:29]
	v_cndmask_b32_e64 v78, v78, v169, s[26:27]
	v_cndmask_b32_e64 v77, v77, v169, s[24:25]
	v_cndmask_b32_e64 v76, v76, v169, s[22:23]
	v_cndmask_b32_e64 v75, v75, v169, s[20:21]
	v_cndmask_b32_e64 v74, v74, v169, s[18:19]
	v_cndmask_b32_e64 v73, v73, v169, s[16:17]
	v_cndmask_b32_e64 v72, v72, v169, s[14:15]
	v_cndmask_b32_e64 v71, v71, v169, s[12:13]
	v_cndmask_b32_e64 v70, v70, v169, s[10:11]
	v_cndmask_b32_e64 v69, v69, v169, s[8:9]
	v_cndmask_b32_e64 v68, v68, v169, s[6:7]
	v_cndmask_b32_e64 v67, v67, v169, s[4:5]
	v_cndmask_b32_e64 v66, v66, v169, s[2:3]
	v_cndmask_b32_e64 v65, v65, v169, s[0:1]
	v_cndmask_b32_e32 v64, v64, v169, vcc
